# GEMM K-loops (in-proj, out-proj): loop-control SALU moved above the loop-back barrier (back-edge rotation)
# baseline (speedup 1.0000x reference)
.LBB0_358:
	s_add_u32 s16, s4, 0xfffc0080
	s_addc_u32 s17, s5, -1
	s_add_i32 s26, 0, 0x10000
	s_cmp_eq_u32 vcc_hi, 12
	s_cselect_b32 s63, s25, s17
	s_cselect_b32 s62, s55, s16
	v_add_u32_e32 v148, s26, v152
	s_cselect_b32 s61, s53, vcc_lo
	s_cselect_b32 s60, s64, s65
	s_add_i32 s27, 0, 0x14000
	ds_read_b128 v[136:139], v148
	ds_read_b128 v[140:143], v148 offset:1024
	ds_read_b128 v[144:147], v148 offset:2048
	ds_read_b128 v[154:157], v148 offset:3072
	v_add_u32_e32 v148, s27, v152
	ds_read_b128 v[158:161], v148
	ds_read_b128 v[162:165], v148 offset:1024
	ds_read_b128 v[178:181], v148 offset:2048
	ds_read_b128 v[182:185], v148 offset:3072
	v_lshl_add_u64 v[148:149], s[4:5], 0, v[132:133]
	s_add_i32 m0, s9, 0xc000
	ds_read_b128 v[186:189], v153
	ds_read_b128 v[190:193], v153 offset:1024
	ds_read_b128 v[194:197], v153 offset:2048
	ds_read_b128 v[198:201], v153 offset:3072
	ds_read_b128 v[202:205], v153 offset:4096
	ds_read_b128 v[206:209], v153 offset:5120
	ds_read_b128 v[210:213], v153 offset:6144
	ds_read_b128 v[222:225], v153 offset:7168
	global_load_lds_dwordx4 v[148:149], off
	v_lshl_add_u64 v[148:149], s[4:5], 0, v[134:135]
	s_add_i32 m0, s9, 0xe000
	s_nop 0
	global_load_lds_dwordx4 v[148:149], off
	s_waitcnt vmcnt(8)
	s_waitcnt lgkmcnt(0)
	s_barrier
	s_setprio 1
	s_waitcnt lgkmcnt(0)
	v_mfma_f32_16x16x32_bf16 v[126:129], v[136:139], v[186:189], v[126:129]
	v_mfma_f32_16x16x32_bf16 v[122:125], v[144:147], v[186:189], v[122:125]
	v_mfma_f32_16x16x32_bf16 v[118:121], v[136:139], v[194:197], v[118:121]
	v_mfma_f32_16x16x32_bf16 v[114:117], v[144:147], v[194:197], v[114:117]
	v_mfma_f32_16x16x32_bf16 v[110:113], v[136:139], v[202:205], v[110:113]
	v_mfma_f32_16x16x32_bf16 v[106:109], v[144:147], v[202:205], v[106:109]
	v_mfma_f32_16x16x32_bf16 v[102:105], v[136:139], v[210:213], v[102:105]
	v_mfma_f32_16x16x32_bf16 v[98:101], v[144:147], v[210:213], v[98:101]
	v_mfma_f32_16x16x32_bf16 v[126:129], v[140:143], v[190:193], v[126:129]
	v_mfma_f32_16x16x32_bf16 v[122:125], v[154:157], v[190:193], v[122:125]
	v_mfma_f32_16x16x32_bf16 v[118:121], v[140:143], v[198:201], v[118:121]
	v_mfma_f32_16x16x32_bf16 v[114:117], v[154:157], v[198:201], v[114:117]
	v_mfma_f32_16x16x32_bf16 v[110:113], v[140:143], v[206:209], v[110:113]
	v_mfma_f32_16x16x32_bf16 v[106:109], v[154:157], v[206:209], v[106:109]
	v_mfma_f32_16x16x32_bf16 v[102:105], v[140:143], v[222:225], v[102:105]
	v_mfma_f32_16x16x32_bf16 v[98:101], v[154:157], v[222:225], v[98:101]
	s_setprio 0
	s_setprio 1
	v_mfma_f32_16x16x32_bf16 v[62:65], v[158:161], v[186:189], v[62:65]
	v_mfma_f32_16x16x32_bf16 v[58:61], v[178:181], v[186:189], v[58:61]
	v_mfma_f32_16x16x32_bf16 v[54:57], v[158:161], v[194:197], v[54:57]
	v_mfma_f32_16x16x32_bf16 v[50:53], v[178:181], v[194:197], v[50:53]
	v_mfma_f32_16x16x32_bf16 v[46:49], v[158:161], v[202:205], v[46:49]
	v_mfma_f32_16x16x32_bf16 v[42:45], v[178:181], v[202:205], v[42:45]
	v_mfma_f32_16x16x32_bf16 v[38:41], v[158:161], v[210:213], v[38:41]
	v_mfma_f32_16x16x32_bf16 v[34:37], v[178:181], v[210:213], v[34:37]
	v_mfma_f32_16x16x32_bf16 v[62:65], v[162:165], v[190:193], v[62:65]
	v_mfma_f32_16x16x32_bf16 v[58:61], v[182:185], v[190:193], v[58:61]
	v_mfma_f32_16x16x32_bf16 v[54:57], v[162:165], v[198:201], v[54:57]
	v_mfma_f32_16x16x32_bf16 v[50:53], v[182:185], v[198:201], v[50:53]
	v_mfma_f32_16x16x32_bf16 v[46:49], v[162:165], v[206:209], v[46:49]
	v_mfma_f32_16x16x32_bf16 v[42:45], v[182:185], v[206:209], v[42:45]
	v_mfma_f32_16x16x32_bf16 v[38:41], v[162:165], v[222:225], v[38:41]
	v_mfma_f32_16x16x32_bf16 v[34:37], v[182:185], v[222:225], v[34:37]
	s_setprio 0
	s_barrier
	s_add_i32 s16, s26, s8
	v_lshl_add_u64 v[148:149], s[60:61], 0, v[12:13]
	s_mov_b32 m0, s16
	ds_read_b128 v[186:189], v153 offset:16384
	ds_read_b128 v[190:193], v153 offset:17408
	ds_read_b128 v[194:197], v153 offset:18432
	ds_read_b128 v[198:201], v153 offset:19456
	ds_read_b128 v[202:205], v153 offset:20480
	ds_read_b128 v[206:209], v153 offset:21504
	ds_read_b128 v[210:213], v153 offset:22528
	ds_read_b128 v[222:225], v153 offset:23552
	global_load_lds_dwordx4 v[148:149], off
	s_add_i32 m0, s16, 0x2000
	s_add_u32 s16, s60, 0x40000
	v_lshl_add_u64 v[168:169], s[60:61], 0, v[130:131]
	s_addc_u32 s17, s61, 0
	s_add_i32 s26, s27, s8
	global_load_lds_dwordx4 v[168:169], off
	v_lshl_add_u64 v[170:171], s[16:17], 0, v[12:13]
	s_mov_b32 m0, s26
	v_lshl_add_u64 v[172:173], s[62:63], 0, v[130:131]
	global_load_lds_dwordx4 v[170:171], off
	v_lshl_add_u64 v[170:171], s[16:17], 0, v[130:131]
	s_add_i32 m0, s26, 0x2000
	s_nop 0
	global_load_lds_dwordx4 v[170:171], off
	v_lshl_add_u64 v[170:171], s[62:63], 0, v[12:13]
	s_mov_b32 m0, s9
	s_nop 0
	global_load_lds_dwordx4 v[170:171], off
	s_mov_b32 m0, s3
	s_nop 0
	global_load_lds_dwordx4 v[172:173], off
	s_waitcnt vmcnt(8)
	s_waitcnt lgkmcnt(0)
	s_barrier
	s_setprio 1
	s_waitcnt lgkmcnt(0)
	v_mfma_f32_16x16x32_bf16 v[94:97], v[136:139], v[186:189], v[94:97]
	v_mfma_f32_16x16x32_bf16 v[90:93], v[144:147], v[186:189], v[90:93]
	v_mfma_f32_16x16x32_bf16 v[86:89], v[136:139], v[194:197], v[86:89]
	v_mfma_f32_16x16x32_bf16 v[82:85], v[144:147], v[194:197], v[82:85]
	v_mfma_f32_16x16x32_bf16 v[78:81], v[136:139], v[202:205], v[78:81]
	v_mfma_f32_16x16x32_bf16 v[74:77], v[144:147], v[202:205], v[74:77]
	v_mfma_f32_16x16x32_bf16 v[70:73], v[136:139], v[210:213], v[70:73]
	v_mfma_f32_16x16x32_bf16 v[66:69], v[144:147], v[210:213], v[66:69]
	v_mfma_f32_16x16x32_bf16 v[94:97], v[140:143], v[190:193], v[94:97]
	v_mfma_f32_16x16x32_bf16 v[90:93], v[154:157], v[190:193], v[90:93]
	v_mfma_f32_16x16x32_bf16 v[86:89], v[140:143], v[198:201], v[86:89]
	v_mfma_f32_16x16x32_bf16 v[82:85], v[154:157], v[198:201], v[82:85]
	v_mfma_f32_16x16x32_bf16 v[78:81], v[140:143], v[206:209], v[78:81]
	v_mfma_f32_16x16x32_bf16 v[74:77], v[154:157], v[206:209], v[74:77]
	v_mfma_f32_16x16x32_bf16 v[70:73], v[140:143], v[222:225], v[70:73]
	v_mfma_f32_16x16x32_bf16 v[66:69], v[154:157], v[222:225], v[66:69]
	s_setprio 0
	s_setprio 1
	v_mfma_f32_16x16x32_bf16 v[30:33], v[158:161], v[186:189], v[30:33]
	v_mfma_f32_16x16x32_bf16 v[26:29], v[178:181], v[186:189], v[26:29]
	v_mfma_f32_16x16x32_bf16 v[22:25], v[158:161], v[194:197], v[22:25]
	v_mfma_f32_16x16x32_bf16 v[18:21], v[178:181], v[194:197], v[18:21]
	v_mfma_f32_16x16x32_bf16 v[14:17], v[158:161], v[202:205], v[14:17]
	v_mfma_f32_16x16x32_bf16 v[8:11], v[178:181], v[202:205], v[8:11]
	v_mfma_f32_16x16x32_bf16 v[4:7], v[158:161], v[210:213], v[4:7]
	v_mfma_f32_16x16x32_bf16 v[0:3], v[178:181], v[210:213], v[0:3]
	v_mfma_f32_16x16x32_bf16 v[30:33], v[162:165], v[190:193], v[30:33]
	v_mfma_f32_16x16x32_bf16 v[26:29], v[182:185], v[190:193], v[26:29]
	v_mfma_f32_16x16x32_bf16 v[22:25], v[162:165], v[198:201], v[22:25]
	v_mfma_f32_16x16x32_bf16 v[18:21], v[182:185], v[198:201], v[18:21]
	v_mfma_f32_16x16x32_bf16 v[14:17], v[162:165], v[206:209], v[14:17]
	v_mfma_f32_16x16x32_bf16 v[8:11], v[182:185], v[206:209], v[8:11]
	v_mfma_f32_16x16x32_bf16 v[4:7], v[162:165], v[222:225], v[4:7]
	v_mfma_f32_16x16x32_bf16 v[0:3], v[182:185], v[222:225], v[0:3]
	s_setprio 0
	s_barrier
	s_add_i32 s26, 0, 0x18000
	s_add_i32 s27, 0, 0x1c000
	v_add_u32_e32 v154, s26, v152
	v_add_u32_e32 v174, s27, v152
	ds_read_b128 v[136:139], v154
	ds_read_b128 v[140:143], v154 offset:1024
	ds_read_b128 v[144:147], v154 offset:2048
	ds_read_b128 v[154:157], v154 offset:3072
	ds_read_b128 v[158:161], v174
	ds_read_b128 v[162:165], v174 offset:1024
	ds_read_b128 v[178:181], v174 offset:2048
	ds_read_b128 v[182:185], v174 offset:3072
	s_add_u32 s16, s62, 0x40000
	s_addc_u32 s17, s63, 0
	s_mov_b32 m0, s6
	v_lshl_add_u64 v[174:175], s[16:17], 0, v[12:13]
	ds_read_b128 v[186:189], v153 offset:32768
	ds_read_b128 v[190:193], v153 offset:33792
	ds_read_b128 v[194:197], v153 offset:34816
	ds_read_b128 v[198:201], v153 offset:35840
	ds_read_b128 v[202:205], v153 offset:36864
	ds_read_b128 v[206:209], v153 offset:37888
	ds_read_b128 v[210:213], v153 offset:38912
	ds_read_b128 v[222:225], v153 offset:39936
	global_load_lds_dwordx4 v[174:175], off
	v_lshl_add_u64 v[174:175], s[16:17], 0, v[130:131]
	s_mov_b32 m0, s7
	s_nop 0
	global_load_lds_dwordx4 v[174:175], off
	s_waitcnt vmcnt(8)
	s_waitcnt lgkmcnt(0)
	s_barrier
	s_setprio 1
	s_waitcnt lgkmcnt(0)
	v_mfma_f32_16x16x32_bf16 v[126:129], v[136:139], v[186:189], v[126:129]
	v_mfma_f32_16x16x32_bf16 v[122:125], v[144:147], v[186:189], v[122:125]
	v_mfma_f32_16x16x32_bf16 v[118:121], v[136:139], v[194:197], v[118:121]
	v_mfma_f32_16x16x32_bf16 v[114:117], v[144:147], v[194:197], v[114:117]
	v_mfma_f32_16x16x32_bf16 v[110:113], v[136:139], v[202:205], v[110:113]
	v_mfma_f32_16x16x32_bf16 v[106:109], v[144:147], v[202:205], v[106:109]
	v_mfma_f32_16x16x32_bf16 v[102:105], v[136:139], v[210:213], v[102:105]
	v_mfma_f32_16x16x32_bf16 v[98:101], v[144:147], v[210:213], v[98:101]
	v_mfma_f32_16x16x32_bf16 v[126:129], v[140:143], v[190:193], v[126:129]
	v_mfma_f32_16x16x32_bf16 v[122:125], v[154:157], v[190:193], v[122:125]
	v_mfma_f32_16x16x32_bf16 v[118:121], v[140:143], v[198:201], v[118:121]
	v_mfma_f32_16x16x32_bf16 v[114:117], v[154:157], v[198:201], v[114:117]
	v_mfma_f32_16x16x32_bf16 v[110:113], v[140:143], v[206:209], v[110:113]
	v_mfma_f32_16x16x32_bf16 v[106:109], v[154:157], v[206:209], v[106:109]
	v_mfma_f32_16x16x32_bf16 v[102:105], v[140:143], v[222:225], v[102:105]
	v_mfma_f32_16x16x32_bf16 v[98:101], v[154:157], v[222:225], v[98:101]
	s_setprio 0
	s_setprio 1
	v_mfma_f32_16x16x32_bf16 v[62:65], v[158:161], v[186:189], v[62:65]
	v_mfma_f32_16x16x32_bf16 v[58:61], v[178:181], v[186:189], v[58:61]
	v_mfma_f32_16x16x32_bf16 v[54:57], v[158:161], v[194:197], v[54:57]
	v_mfma_f32_16x16x32_bf16 v[50:53], v[178:181], v[194:197], v[50:53]
	v_mfma_f32_16x16x32_bf16 v[46:49], v[158:161], v[202:205], v[46:49]
	v_mfma_f32_16x16x32_bf16 v[42:45], v[178:181], v[202:205], v[42:45]
	v_mfma_f32_16x16x32_bf16 v[38:41], v[158:161], v[210:213], v[38:41]
	v_mfma_f32_16x16x32_bf16 v[34:37], v[178:181], v[210:213], v[34:37]
	v_mfma_f32_16x16x32_bf16 v[62:65], v[162:165], v[190:193], v[62:65]
	v_mfma_f32_16x16x32_bf16 v[58:61], v[182:185], v[190:193], v[58:61]
	v_mfma_f32_16x16x32_bf16 v[54:57], v[162:165], v[198:201], v[54:57]
	v_mfma_f32_16x16x32_bf16 v[50:53], v[182:185], v[198:201], v[50:53]
	v_mfma_f32_16x16x32_bf16 v[46:49], v[162:165], v[206:209], v[46:49]
	v_mfma_f32_16x16x32_bf16 v[42:45], v[182:185], v[206:209], v[42:45]
	v_mfma_f32_16x16x32_bf16 v[38:41], v[162:165], v[222:225], v[38:41]
	v_mfma_f32_16x16x32_bf16 v[34:37], v[182:185], v[222:225], v[34:37]
	s_setprio 0
	s_barrier
	s_add_i32 s16, s26, s8
	v_lshl_add_u64 v[148:149], v[148:149], 0, s[42:43]
	s_mov_b32 m0, s16
	ds_read_b128 v[186:189], v153 offset:49152
	ds_read_b128 v[190:193], v153 offset:50176
	ds_read_b128 v[194:197], v153 offset:51200
	ds_read_b128 v[198:201], v153 offset:52224
	ds_read_b128 v[202:205], v153 offset:53248
	ds_read_b128 v[206:209], v153 offset:54272
	ds_read_b128 v[210:213], v153 offset:55296
	ds_read_b128 v[222:225], v153 offset:56320
	global_load_lds_dwordx4 v[148:149], off
	s_add_i32 m0, s16, 0x2000
	s_add_u32 s16, s60, 0x40080
	v_lshl_add_u64 v[148:149], v[168:169], 0, s[42:43]
	s_addc_u32 s17, s61, 0
	s_add_i32 s26, s27, s8
	global_load_lds_dwordx4 v[148:149], off
	v_lshl_add_u64 v[148:149], s[16:17], 0, v[12:13]
	s_mov_b32 m0, s26
	s_nop 0
	global_load_lds_dwordx4 v[148:149], off
	v_lshl_add_u64 v[148:149], s[16:17], 0, v[130:131]
	s_add_i32 m0, s26, 0x2000
	s_nop 0
	global_load_lds_dwordx4 v[148:149], off
	v_lshl_add_u64 v[148:149], v[170:171], 0, s[42:43]
	s_mov_b32 m0, s35
	s_nop 0
	global_load_lds_dwordx4 v[148:149], off
	v_lshl_add_u64 v[148:149], v[172:173], 0, s[42:43]
	s_mov_b32 m0, s38
	s_nop 0
	global_load_lds_dwordx4 v[148:149], off
	s_waitcnt vmcnt(8)
	s_waitcnt lgkmcnt(0)
	s_barrier
	s_setprio 1
	s_waitcnt lgkmcnt(0)
	v_mfma_f32_16x16x32_bf16 v[94:97], v[136:139], v[186:189], v[94:97]
	v_mfma_f32_16x16x32_bf16 v[90:93], v[144:147], v[186:189], v[90:93]
	v_mfma_f32_16x16x32_bf16 v[86:89], v[136:139], v[194:197], v[86:89]
	v_mfma_f32_16x16x32_bf16 v[82:85], v[144:147], v[194:197], v[82:85]
	v_mfma_f32_16x16x32_bf16 v[78:81], v[136:139], v[202:205], v[78:81]
	v_mfma_f32_16x16x32_bf16 v[74:77], v[144:147], v[202:205], v[74:77]
	v_mfma_f32_16x16x32_bf16 v[70:73], v[136:139], v[210:213], v[70:73]
	v_mfma_f32_16x16x32_bf16 v[66:69], v[144:147], v[210:213], v[66:69]
	v_mfma_f32_16x16x32_bf16 v[94:97], v[140:143], v[190:193], v[94:97]
	v_mfma_f32_16x16x32_bf16 v[90:93], v[154:157], v[190:193], v[90:93]
	v_mfma_f32_16x16x32_bf16 v[86:89], v[140:143], v[198:201], v[86:89]
	v_mfma_f32_16x16x32_bf16 v[82:85], v[154:157], v[198:201], v[82:85]
	v_mfma_f32_16x16x32_bf16 v[78:81], v[140:143], v[206:209], v[78:81]
	v_mfma_f32_16x16x32_bf16 v[74:77], v[154:157], v[206:209], v[74:77]
	v_mfma_f32_16x16x32_bf16 v[70:73], v[140:143], v[222:225], v[70:73]
	v_mfma_f32_16x16x32_bf16 v[66:69], v[154:157], v[222:225], v[66:69]
	s_setprio 0
	s_setprio 1
	v_mfma_f32_16x16x32_bf16 v[30:33], v[158:161], v[186:189], v[30:33]
	v_mfma_f32_16x16x32_bf16 v[26:29], v[178:181], v[186:189], v[26:29]
	v_mfma_f32_16x16x32_bf16 v[22:25], v[158:161], v[194:197], v[22:25]
	v_mfma_f32_16x16x32_bf16 v[18:21], v[178:181], v[194:197], v[18:21]
	v_mfma_f32_16x16x32_bf16 v[14:17], v[158:161], v[202:205], v[14:17]
	v_mfma_f32_16x16x32_bf16 v[8:11], v[178:181], v[202:205], v[8:11]
	v_mfma_f32_16x16x32_bf16 v[4:7], v[158:161], v[210:213], v[4:7]
	v_mfma_f32_16x16x32_bf16 v[0:3], v[178:181], v[210:213], v[0:3]
	v_mfma_f32_16x16x32_bf16 v[30:33], v[162:165], v[190:193], v[30:33]
	v_mfma_f32_16x16x32_bf16 v[26:29], v[182:185], v[190:193], v[26:29]
	v_mfma_f32_16x16x32_bf16 v[22:25], v[162:165], v[198:201], v[22:25]
	v_mfma_f32_16x16x32_bf16 v[18:21], v[182:185], v[198:201], v[18:21]
	v_mfma_f32_16x16x32_bf16 v[14:17], v[162:165], v[206:209], v[14:17]
	v_mfma_f32_16x16x32_bf16 v[8:11], v[182:185], v[206:209], v[8:11]
	v_mfma_f32_16x16x32_bf16 v[4:7], v[162:165], v[222:225], v[4:7]
	v_mfma_f32_16x16x32_bf16 v[0:3], v[182:185], v[222:225], v[0:3]
	s_setprio 0
	s_add_i32 vcc_hi, vcc_hi, 2
	s_add_u32 s4, s4, 0x100
	s_addc_u32 s5, s5, 0
	s_add_u32 s65, s65, 0x100
	s_addc_u32 vcc_lo, vcc_lo, 0
	s_cmp_gt_u32 vcc_hi, 13
	s_barrier
	s_cbranch_scc0 .LBB0_358
	s_and_b64 vcc, exec, s[10:11]
	s_cbranch_vccz .LBB0_361
	s_barrier

.LBB0_842:
	s_add_u32 s16, s52, 0xfffc0080
	s_addc_u32 s17, s53, -1
	s_add_i32 s26, 0, 0x10000
	s_cmp_eq_u32 vcc_hi, 12
	s_cselect_b32 s57, s11, s17
	s_cselect_b32 s56, s66, s16
	s_cselect_b32 s55, s9, vcc_lo
	s_cselect_b32 s54, s67, s74
	s_add_i32 s27, 0, 0x14000
	v_add_u32_e32 v142, s26, v208
	v_add_u32_e32 v158, s27, v208
	ds_read_b128 v[130:133], v142
	ds_read_b128 v[134:137], v142 offset:1024
	ds_read_b128 v[138:141], v142 offset:2048
	ds_read_b128 v[142:145], v142 offset:3072
	ds_read_b128 v[146:149], v158
	ds_read_b128 v[150:153], v158 offset:1024
	ds_read_b128 v[154:157], v158 offset:2048
	ds_read_b128 v[158:161], v158 offset:3072
	v_lshl_add_u64 v[176:177], s[52:53], 0, v[180:181]
	s_add_i32 m0, s35, 0xc000
	ds_read_b128 v[162:165], v209
	ds_read_b128 v[168:171], v209 offset:1024
	ds_read_b128 v[172:175], v209 offset:2048
	ds_read_b128 v[184:187], v209 offset:3072
	ds_read_b128 v[188:191], v209 offset:4096
	ds_read_b128 v[192:195], v209 offset:5120
	ds_read_b128 v[196:199], v209 offset:6144
	ds_read_b128 v[200:203], v209 offset:7168
	global_load_lds_dwordx4 v[176:177], off
	v_lshl_add_u64 v[176:177], s[52:53], 0, v[182:183]
	s_add_i32 m0, s35, 0xe000
	s_nop 0
	global_load_lds_dwordx4 v[176:177], off
	s_waitcnt vmcnt(8)
	s_waitcnt lgkmcnt(0)
	s_barrier
	s_setprio 1
	s_waitcnt lgkmcnt(0)
	v_mfma_f32_16x16x32_bf16 v[126:129], v[130:133], v[162:165], v[126:129]
	v_mfma_f32_16x16x32_bf16 v[122:125], v[138:141], v[162:165], v[122:125]
	v_mfma_f32_16x16x32_bf16 v[118:121], v[130:133], v[172:175], v[118:121]
	v_mfma_f32_16x16x32_bf16 v[114:117], v[138:141], v[172:175], v[114:117]
	v_mfma_f32_16x16x32_bf16 v[110:113], v[130:133], v[188:191], v[110:113]
	v_mfma_f32_16x16x32_bf16 v[106:109], v[138:141], v[188:191], v[106:109]
	v_mfma_f32_16x16x32_bf16 v[102:105], v[130:133], v[196:199], v[102:105]
	v_mfma_f32_16x16x32_bf16 v[98:101], v[138:141], v[196:199], v[98:101]
	v_mfma_f32_16x16x32_bf16 v[126:129], v[134:137], v[168:171], v[126:129]
	v_mfma_f32_16x16x32_bf16 v[122:125], v[142:145], v[168:171], v[122:125]
	v_mfma_f32_16x16x32_bf16 v[118:121], v[134:137], v[184:187], v[118:121]
	v_mfma_f32_16x16x32_bf16 v[114:117], v[142:145], v[184:187], v[114:117]
	v_mfma_f32_16x16x32_bf16 v[110:113], v[134:137], v[192:195], v[110:113]
	v_mfma_f32_16x16x32_bf16 v[106:109], v[142:145], v[192:195], v[106:109]
	v_mfma_f32_16x16x32_bf16 v[102:105], v[134:137], v[200:203], v[102:105]
	v_mfma_f32_16x16x32_bf16 v[98:101], v[142:145], v[200:203], v[98:101]
	s_setprio 0
	s_setprio 1
	v_mfma_f32_16x16x32_bf16 v[66:69], v[146:149], v[162:165], v[66:69]
	v_mfma_f32_16x16x32_bf16 v[58:61], v[154:157], v[162:165], v[58:61]
	v_mfma_f32_16x16x32_bf16 v[54:57], v[146:149], v[172:175], v[54:57]
	v_mfma_f32_16x16x32_bf16 v[50:53], v[154:157], v[172:175], v[50:53]
	v_mfma_f32_16x16x32_bf16 v[46:49], v[146:149], v[188:191], v[46:49]
	v_mfma_f32_16x16x32_bf16 v[42:45], v[154:157], v[188:191], v[42:45]
	v_mfma_f32_16x16x32_bf16 v[38:41], v[146:149], v[196:199], v[38:41]
	v_mfma_f32_16x16x32_bf16 v[34:37], v[154:157], v[196:199], v[34:37]
	v_mfma_f32_16x16x32_bf16 v[66:69], v[150:153], v[168:171], v[66:69]
	v_mfma_f32_16x16x32_bf16 v[58:61], v[158:161], v[168:171], v[58:61]
	v_mfma_f32_16x16x32_bf16 v[54:57], v[150:153], v[184:187], v[54:57]
	v_mfma_f32_16x16x32_bf16 v[50:53], v[158:161], v[184:187], v[50:53]
	v_mfma_f32_16x16x32_bf16 v[46:49], v[150:153], v[192:195], v[46:49]
	v_mfma_f32_16x16x32_bf16 v[42:45], v[158:161], v[192:195], v[42:45]
	v_mfma_f32_16x16x32_bf16 v[38:41], v[150:153], v[200:203], v[38:41]
	v_mfma_f32_16x16x32_bf16 v[34:37], v[158:161], v[200:203], v[34:37]
	s_setprio 0
	s_barrier
	s_add_i32 s16, s26, s34
	v_lshl_add_u64 v[176:177], s[54:55], 0, v[12:13]
	s_mov_b32 m0, s16
	ds_read_b128 v[162:165], v209 offset:16384
	ds_read_b128 v[168:171], v209 offset:17408
	ds_read_b128 v[172:175], v209 offset:18432
	ds_read_b128 v[184:187], v209 offset:19456
	ds_read_b128 v[188:191], v209 offset:20480
	ds_read_b128 v[192:195], v209 offset:21504
	ds_read_b128 v[196:199], v209 offset:22528
	ds_read_b128 v[200:203], v209 offset:23552
	global_load_lds_dwordx4 v[176:177], off
	s_add_i32 m0, s16, 0x2000
	s_add_u32 s16, s54, 0x40000
	v_lshl_add_u64 v[204:205], s[54:55], 0, v[178:179]
	s_addc_u32 s17, s55, 0
	s_add_i32 s26, s27, s34
	global_load_lds_dwordx4 v[204:205], off
	v_lshl_add_u64 v[210:211], s[16:17], 0, v[12:13]
	s_mov_b32 m0, s26
	v_lshl_add_u64 v[212:213], s[56:57], 0, v[178:179]
	global_load_lds_dwordx4 v[210:211], off
	v_lshl_add_u64 v[210:211], s[16:17], 0, v[178:179]
	s_add_i32 m0, s26, 0x2000
	s_nop 0
	global_load_lds_dwordx4 v[210:211], off
	v_lshl_add_u64 v[210:211], s[56:57], 0, v[12:13]
	s_mov_b32 m0, s35
	s_nop 0
	global_load_lds_dwordx4 v[210:211], off
	s_mov_b32 m0, s38
	s_nop 0
	global_load_lds_dwordx4 v[212:213], off
	s_waitcnt vmcnt(8)
	s_waitcnt lgkmcnt(0)
	s_barrier
	s_setprio 1
	s_waitcnt lgkmcnt(0)
	v_mfma_f32_16x16x32_bf16 v[94:97], v[130:133], v[162:165], v[94:97]
	v_mfma_f32_16x16x32_bf16 v[90:93], v[138:141], v[162:165], v[90:93]
	v_mfma_f32_16x16x32_bf16 v[86:89], v[130:133], v[172:175], v[86:89]
	v_mfma_f32_16x16x32_bf16 v[82:85], v[138:141], v[172:175], v[82:85]
	v_mfma_f32_16x16x32_bf16 v[78:81], v[130:133], v[188:191], v[78:81]
	v_mfma_f32_16x16x32_bf16 v[74:77], v[138:141], v[188:191], v[74:77]
	v_mfma_f32_16x16x32_bf16 v[70:73], v[130:133], v[196:199], v[70:73]
	v_mfma_f32_16x16x32_bf16 v[62:65], v[138:141], v[196:199], v[62:65]
	v_mfma_f32_16x16x32_bf16 v[94:97], v[134:137], v[168:171], v[94:97]
	v_mfma_f32_16x16x32_bf16 v[90:93], v[142:145], v[168:171], v[90:93]
	v_mfma_f32_16x16x32_bf16 v[86:89], v[134:137], v[184:187], v[86:89]
	v_mfma_f32_16x16x32_bf16 v[82:85], v[142:145], v[184:187], v[82:85]
	v_mfma_f32_16x16x32_bf16 v[78:81], v[134:137], v[192:195], v[78:81]
	v_mfma_f32_16x16x32_bf16 v[74:77], v[142:145], v[192:195], v[74:77]
	v_mfma_f32_16x16x32_bf16 v[70:73], v[134:137], v[200:203], v[70:73]
	v_mfma_f32_16x16x32_bf16 v[62:65], v[142:145], v[200:203], v[62:65]
	s_setprio 0
	s_setprio 1
	v_mfma_f32_16x16x32_bf16 v[30:33], v[146:149], v[162:165], v[30:33]
	v_mfma_f32_16x16x32_bf16 v[26:29], v[154:157], v[162:165], v[26:29]
	v_mfma_f32_16x16x32_bf16 v[22:25], v[146:149], v[172:175], v[22:25]
	v_mfma_f32_16x16x32_bf16 v[18:21], v[154:157], v[172:175], v[18:21]
	v_mfma_f32_16x16x32_bf16 v[14:17], v[146:149], v[188:191], v[14:17]
	v_mfma_f32_16x16x32_bf16 v[8:11], v[154:157], v[188:191], v[8:11]
	v_mfma_f32_16x16x32_bf16 v[4:7], v[146:149], v[196:199], v[4:7]
	v_mfma_f32_16x16x32_bf16 v[0:3], v[154:157], v[196:199], v[0:3]
	v_mfma_f32_16x16x32_bf16 v[30:33], v[150:153], v[168:171], v[30:33]
	v_mfma_f32_16x16x32_bf16 v[26:29], v[158:161], v[168:171], v[26:29]
	v_mfma_f32_16x16x32_bf16 v[22:25], v[150:153], v[184:187], v[22:25]
	v_mfma_f32_16x16x32_bf16 v[18:21], v[158:161], v[184:187], v[18:21]
	v_mfma_f32_16x16x32_bf16 v[14:17], v[150:153], v[192:195], v[14:17]
	v_mfma_f32_16x16x32_bf16 v[8:11], v[158:161], v[192:195], v[8:11]
	v_mfma_f32_16x16x32_bf16 v[4:7], v[150:153], v[200:203], v[4:7]
	v_mfma_f32_16x16x32_bf16 v[0:3], v[158:161], v[200:203], v[0:3]
	s_setprio 0
	s_barrier
	s_add_i32 s26, 0, 0x18000
	s_add_i32 s27, 0, 0x1c000
	v_add_u32_e32 v142, s26, v208
	v_add_u32_e32 v158, s27, v208
	ds_read_b128 v[130:133], v142
	ds_read_b128 v[134:137], v142 offset:1024
	ds_read_b128 v[138:141], v142 offset:2048
	ds_read_b128 v[142:145], v142 offset:3072
	ds_read_b128 v[146:149], v158
	ds_read_b128 v[150:153], v158 offset:1024
	ds_read_b128 v[154:157], v158 offset:2048
	ds_read_b128 v[158:161], v158 offset:3072
	s_add_u32 s16, s56, 0x40000
	s_addc_u32 s17, s57, 0
	s_mov_b32 m0, s39
	v_lshl_add_u64 v[214:215], s[16:17], 0, v[12:13]
	ds_read_b128 v[162:165], v209 offset:32768
	ds_read_b128 v[168:171], v209 offset:33792
	ds_read_b128 v[172:175], v209 offset:34816
	ds_read_b128 v[184:187], v209 offset:35840
	ds_read_b128 v[188:191], v209 offset:36864
	ds_read_b128 v[192:195], v209 offset:37888
	ds_read_b128 v[196:199], v209 offset:38912
	ds_read_b128 v[200:203], v209 offset:39936
	global_load_lds_dwordx4 v[214:215], off
	v_lshl_add_u64 v[214:215], s[16:17], 0, v[178:179]
	s_mov_b32 m0, s40
	s_nop 0
	global_load_lds_dwordx4 v[214:215], off
	s_waitcnt vmcnt(8)
	s_waitcnt lgkmcnt(0)
	s_barrier
	s_setprio 1
	s_waitcnt lgkmcnt(0)
	v_mfma_f32_16x16x32_bf16 v[126:129], v[130:133], v[162:165], v[126:129]
	v_mfma_f32_16x16x32_bf16 v[122:125], v[138:141], v[162:165], v[122:125]
	v_mfma_f32_16x16x32_bf16 v[118:121], v[130:133], v[172:175], v[118:121]
	v_mfma_f32_16x16x32_bf16 v[114:117], v[138:141], v[172:175], v[114:117]
	v_mfma_f32_16x16x32_bf16 v[110:113], v[130:133], v[188:191], v[110:113]
	v_mfma_f32_16x16x32_bf16 v[106:109], v[138:141], v[188:191], v[106:109]
	v_mfma_f32_16x16x32_bf16 v[102:105], v[130:133], v[196:199], v[102:105]
	v_mfma_f32_16x16x32_bf16 v[98:101], v[138:141], v[196:199], v[98:101]
	v_mfma_f32_16x16x32_bf16 v[126:129], v[134:137], v[168:171], v[126:129]
	v_mfma_f32_16x16x32_bf16 v[122:125], v[142:145], v[168:171], v[122:125]
	v_mfma_f32_16x16x32_bf16 v[118:121], v[134:137], v[184:187], v[118:121]
	v_mfma_f32_16x16x32_bf16 v[114:117], v[142:145], v[184:187], v[114:117]
	v_mfma_f32_16x16x32_bf16 v[110:113], v[134:137], v[192:195], v[110:113]
	v_mfma_f32_16x16x32_bf16 v[106:109], v[142:145], v[192:195], v[106:109]
	v_mfma_f32_16x16x32_bf16 v[102:105], v[134:137], v[200:203], v[102:105]
	v_mfma_f32_16x16x32_bf16 v[98:101], v[142:145], v[200:203], v[98:101]
	s_setprio 0
	s_setprio 1
	v_mfma_f32_16x16x32_bf16 v[66:69], v[146:149], v[162:165], v[66:69]
	v_mfma_f32_16x16x32_bf16 v[58:61], v[154:157], v[162:165], v[58:61]
	v_mfma_f32_16x16x32_bf16 v[54:57], v[146:149], v[172:175], v[54:57]
	v_mfma_f32_16x16x32_bf16 v[50:53], v[154:157], v[172:175], v[50:53]
	v_mfma_f32_16x16x32_bf16 v[46:49], v[146:149], v[188:191], v[46:49]
	v_mfma_f32_16x16x32_bf16 v[42:45], v[154:157], v[188:191], v[42:45]
	v_mfma_f32_16x16x32_bf16 v[38:41], v[146:149], v[196:199], v[38:41]
	v_mfma_f32_16x16x32_bf16 v[34:37], v[154:157], v[196:199], v[34:37]
	v_mfma_f32_16x16x32_bf16 v[66:69], v[150:153], v[168:171], v[66:69]
	v_mfma_f32_16x16x32_bf16 v[58:61], v[158:161], v[168:171], v[58:61]
	v_mfma_f32_16x16x32_bf16 v[54:57], v[150:153], v[184:187], v[54:57]
	v_mfma_f32_16x16x32_bf16 v[50:53], v[158:161], v[184:187], v[50:53]
	v_mfma_f32_16x16x32_bf16 v[46:49], v[150:153], v[192:195], v[46:49]
	v_mfma_f32_16x16x32_bf16 v[42:45], v[158:161], v[192:195], v[42:45]
	v_mfma_f32_16x16x32_bf16 v[38:41], v[150:153], v[200:203], v[38:41]
	v_mfma_f32_16x16x32_bf16 v[34:37], v[158:161], v[200:203], v[34:37]
	s_setprio 0
	s_barrier
	s_add_i32 s16, s26, s34
	v_lshl_add_u64 v[176:177], v[176:177], 0, s[42:43]
	s_mov_b32 m0, s16
	ds_read_b128 v[162:165], v209 offset:49152
	ds_read_b128 v[168:171], v209 offset:50176
	ds_read_b128 v[172:175], v209 offset:51200
	ds_read_b128 v[184:187], v209 offset:52224
	ds_read_b128 v[188:191], v209 offset:53248
	ds_read_b128 v[192:195], v209 offset:54272
	ds_read_b128 v[196:199], v209 offset:55296
	ds_read_b128 v[200:203], v209 offset:56320
	global_load_lds_dwordx4 v[176:177], off
	s_add_i32 m0, s16, 0x2000
	s_add_u32 s16, s54, 0x40080
	v_lshl_add_u64 v[176:177], v[204:205], 0, s[42:43]
	s_addc_u32 s17, s55, 0
	s_add_i32 s26, s27, s34
	global_load_lds_dwordx4 v[176:177], off
	v_lshl_add_u64 v[176:177], s[16:17], 0, v[12:13]
	s_mov_b32 m0, s26
	s_nop 0
	global_load_lds_dwordx4 v[176:177], off
	v_lshl_add_u64 v[176:177], s[16:17], 0, v[178:179]
	s_add_i32 m0, s26, 0x2000
	s_nop 0
	global_load_lds_dwordx4 v[176:177], off
	v_lshl_add_u64 v[176:177], v[210:211], 0, s[42:43]
	s_mov_b32 m0, s61
	s_nop 0
	global_load_lds_dwordx4 v[176:177], off
	v_lshl_add_u64 v[176:177], v[212:213], 0, s[42:43]
	s_mov_b32 m0, s62
	s_nop 0
	global_load_lds_dwordx4 v[176:177], off
	s_waitcnt vmcnt(8)
	s_waitcnt lgkmcnt(0)
	s_barrier
	s_setprio 1
	s_waitcnt lgkmcnt(0)
	v_mfma_f32_16x16x32_bf16 v[94:97], v[130:133], v[162:165], v[94:97]
	v_mfma_f32_16x16x32_bf16 v[90:93], v[138:141], v[162:165], v[90:93]
	v_mfma_f32_16x16x32_bf16 v[86:89], v[130:133], v[172:175], v[86:89]
	v_mfma_f32_16x16x32_bf16 v[82:85], v[138:141], v[172:175], v[82:85]
	v_mfma_f32_16x16x32_bf16 v[78:81], v[130:133], v[188:191], v[78:81]
	v_mfma_f32_16x16x32_bf16 v[74:77], v[138:141], v[188:191], v[74:77]
	v_mfma_f32_16x16x32_bf16 v[70:73], v[130:133], v[196:199], v[70:73]
	v_mfma_f32_16x16x32_bf16 v[62:65], v[138:141], v[196:199], v[62:65]
	v_mfma_f32_16x16x32_bf16 v[94:97], v[134:137], v[168:171], v[94:97]
	v_mfma_f32_16x16x32_bf16 v[90:93], v[142:145], v[168:171], v[90:93]
	v_mfma_f32_16x16x32_bf16 v[86:89], v[134:137], v[184:187], v[86:89]
	v_mfma_f32_16x16x32_bf16 v[82:85], v[142:145], v[184:187], v[82:85]
	v_mfma_f32_16x16x32_bf16 v[78:81], v[134:137], v[192:195], v[78:81]
	v_mfma_f32_16x16x32_bf16 v[74:77], v[142:145], v[192:195], v[74:77]
	v_mfma_f32_16x16x32_bf16 v[70:73], v[134:137], v[200:203], v[70:73]
	v_mfma_f32_16x16x32_bf16 v[62:65], v[142:145], v[200:203], v[62:65]
	s_setprio 0
	s_setprio 1
	v_mfma_f32_16x16x32_bf16 v[30:33], v[146:149], v[162:165], v[30:33]
	v_mfma_f32_16x16x32_bf16 v[26:29], v[154:157], v[162:165], v[26:29]
	v_mfma_f32_16x16x32_bf16 v[22:25], v[146:149], v[172:175], v[22:25]
	v_mfma_f32_16x16x32_bf16 v[18:21], v[154:157], v[172:175], v[18:21]
	v_mfma_f32_16x16x32_bf16 v[14:17], v[146:149], v[188:191], v[14:17]
	v_mfma_f32_16x16x32_bf16 v[8:11], v[154:157], v[188:191], v[8:11]
	v_mfma_f32_16x16x32_bf16 v[4:7], v[146:149], v[196:199], v[4:7]
	v_mfma_f32_16x16x32_bf16 v[0:3], v[154:157], v[196:199], v[0:3]
	v_mfma_f32_16x16x32_bf16 v[30:33], v[150:153], v[168:171], v[30:33]
	v_mfma_f32_16x16x32_bf16 v[26:29], v[158:161], v[168:171], v[26:29]
	v_mfma_f32_16x16x32_bf16 v[22:25], v[150:153], v[184:187], v[22:25]
	v_mfma_f32_16x16x32_bf16 v[18:21], v[158:161], v[184:187], v[18:21]
	v_mfma_f32_16x16x32_bf16 v[14:17], v[150:153], v[192:195], v[14:17]
	v_mfma_f32_16x16x32_bf16 v[8:11], v[158:161], v[192:195], v[8:11]
	v_mfma_f32_16x16x32_bf16 v[4:7], v[150:153], v[200:203], v[4:7]
	v_mfma_f32_16x16x32_bf16 v[0:3], v[158:161], v[200:203], v[0:3]
	s_setprio 0
	s_add_i32 vcc_hi, vcc_hi, 2
	s_add_u32 s52, s52, 0x100
	s_addc_u32 s53, s53, 0
	s_add_u32 s74, s74, 0x100
	s_addc_u32 vcc_lo, vcc_lo, 0
	s_cmp_gt_u32 vcc_hi, 13
	s_barrier
	s_cbranch_scc0 .LBB0_842
	s_and_b64 vcc, exec, s[6:7]
	s_cbranch_vccz .LBB0_845
	s_barrier
